# uq/ukv GEMM loop: first K-loop trip peeled with C = 0 MFMAs, per-tile accumulator zeroing removed (same lever as the other four GEMM loops)
# baseline (speedup 1.0000x reference)
; #define PG8_STAGE(bufoff, gbase, voff) do { _Pragma("unroll") for (int _i = 0; _i < 2; ++_i) \
;         __builtin_amdgcn_global_load_lds((const unsigned*)((const char*)(gbase) + (voff)[_i]), (LAS unsigned*)(lds + (bufoff) + ldsw + _i * 8192), 16, 0, 0); } while (0)
; #define PG8_LDA(dst, b, h) do { _Pragma("unroll") for (int m = 0; m < 4; ++m) _Pragma("unroll") for (int k = 0; k < 2; ++k) dst[m][k] = *(const LAS bf16x8*)(lds + PG8_SA(b, h) + aoff + m * 2048 + k * 1024); } while (0)
; #define PG8_LDB(dst, b, h) do { _Pragma("unroll") for (int n = 0; n < 2; ++n) _Pragma("unroll") for (int k = 0; k < 2; ++k) dst[n][k] = *(const LAS bf16x8*)(lds + PG8_SB(b, h) + boff + n * 2048 + k * 1024); } while (0)
; #define PG8_WAIT_V(n) asm volatile("s_waitcnt vmcnt(" #n ")" ::: "memory")
; #define PG8_WAIT_L(n) asm volatile("s_waitcnt lgkmcnt(" #n ")" ::: "memory")
; #define PG8_BAR __builtin_amdgcn_s_barrier()
; #define PG8_SCHED __builtin_amdgcn_sched_barrier(0)
; template <class Epi, bool SEG>
; __device__ __forceinline__ void gemm_phase(LAS unsigned char* lds, const Gemm g, const int G, const int cidx, const Epi& E) {
;     ...
;     f32x4 acc[2][2][4][2];
; #pragma unroll
;     for (int a = 0; a < 2; ++a)
; #pragma unroll
;         for (int b = 0; b < 2; ++b)
; #pragma unroll
;             for (int m = 0; m < 4; ++m)
; #pragma unroll
;                 for (int n = 0; n < 2; ++n) acc[a][b][m][n] = (f32x4){0.f, 0.f, 0.f, 0.f};
;     ...
;         for (int t = 0; t < nt; t += 2) {
;             const bool last = (t == nt - 2);
;             const char* a1 = cA + (size_t)(t + 1) * kstep;
;             const char* a2 = last ? nA : cA + (size_t)(t + 2) * kstep; const char* b2 = last ? nB : cB + (size_t)(t + 2) * kstep;
;             const char* a3 = a2 + kstep; const char* b3 = b2 + kstep;
;             PG8_LDB(B0, 0, 0); PG8_LDB(B1, 0, 1); PG8_SCHED; PG8_LDA(At, 0, 0); PG8_STAGE(PG8_SA(1, 1), a1 + hstepA, voffA);
;             PG8_WAIT_V(8); PG8_WAIT_L(0); PG8_BAR; PG8_MMA(0, 0, At, B0); PG8_MMA(0, 1, At, B1); PG8_BAR; PG8_SCHED;
;             PG8_LDA(At, 0, 1); PG8_STAGE(PG8_SB(0, 0), b2, voffB); PG8_STAGE(PG8_SB(0, 1), b2 + hstepB, voffB); PG8_STAGE(PG8_SA(0, 0), a2, voffA);
;             PG8_WAIT_V(8); PG8_WAIT_L(0); PG8_BAR; PG8_MMA(1, 0, At, B0); PG8_MMA(1, 1, At, B1); PG8_BAR; PG8_SCHED;
.LBB0_1059:
	s_add_u32 s61, s42, 0x100
	s_addc_u32 s62, s43, 0
	s_mov_b32 s42, 0
	s_add_i32 s63, s42, 2
	s_add_u32 s40, s22, 0x100
	s_addc_u32 s41, s23, 0
	s_add_i32 s66, 0, 0x10000
	s_cmp_eq_u32 s57, s42
	s_cselect_b32 s43, s19, s41
	s_cselect_b32 s42, s18, s40
	v_add_u32_e32 v145, s66, v142
	s_cselect_b32 s65, s21, s62
	s_cselect_b32 s64, s20, s61
	s_add_i32 s67, 0, 0x14000
	ds_read_b128 v[146:149], v145
	ds_read_b128 v[150:153], v145 offset:1024
	ds_read_b128 v[154:157], v145 offset:2048
	ds_read_b128 v[158:161], v145 offset:3072
	v_add_u32_e32 v145, s67, v142
	ds_read_b128 v[162:165], v145
	ds_read_b128 v[166:169], v145 offset:1024
	ds_read_b128 v[170:173], v145 offset:2048
	ds_read_b128 v[174:177], v145 offset:3072
	v_lshl_add_u64 v[220:221], s[22:23], 0, v[138:139]
	s_add_i32 m0, s47, 0xc000
	ds_read_b128 v[178:181], v144
	ds_read_b128 v[182:185], v144 offset:1024
	ds_read_b128 v[186:189], v144 offset:2048
	ds_read_b128 v[190:193], v144 offset:3072
	ds_read_b128 v[194:197], v144 offset:4096
	ds_read_b128 v[198:201], v144 offset:5120
	ds_read_b128 v[212:215], v144 offset:6144
	ds_read_b128 v[216:219], v144 offset:7168
	global_load_lds_dwordx4 v[220:221], off
	v_lshl_add_u64 v[220:221], s[22:23], 0, v[140:141]
	s_add_i32 m0, s47, 0xe000
	s_nop 0
	global_load_lds_dwordx4 v[220:221], off
	s_waitcnt vmcnt(8)
	s_waitcnt lgkmcnt(0)
	s_setprio 1
	s_barrier
	v_mfma_f32_16x16x32_bf16 v[130:133], v[146:149], v[178:181], 0
	v_mfma_f32_16x16x32_bf16 v[126:129], v[154:157], v[178:181], 0
	v_mfma_f32_16x16x32_bf16 v[122:125], v[146:149], v[186:189], 0
	v_mfma_f32_16x16x32_bf16 v[118:121], v[154:157], v[186:189], 0
	v_mfma_f32_16x16x32_bf16 v[106:109], v[146:149], v[194:197], 0
	v_mfma_f32_16x16x32_bf16 v[102:105], v[154:157], v[194:197], 0
	v_mfma_f32_16x16x32_bf16 v[90:93], v[146:149], v[212:215], 0
	v_mfma_f32_16x16x32_bf16 v[86:89], v[154:157], v[212:215], 0
	v_mfma_f32_16x16x32_bf16 v[130:133], v[150:153], v[182:185], v[130:133]
	v_mfma_f32_16x16x32_bf16 v[126:129], v[158:161], v[182:185], v[126:129]
	v_mfma_f32_16x16x32_bf16 v[122:125], v[150:153], v[190:193], v[122:125]
	v_mfma_f32_16x16x32_bf16 v[118:121], v[158:161], v[190:193], v[118:121]
	v_mfma_f32_16x16x32_bf16 v[106:109], v[150:153], v[198:201], v[106:109]
	v_mfma_f32_16x16x32_bf16 v[102:105], v[158:161], v[198:201], v[102:105]
	v_mfma_f32_16x16x32_bf16 v[90:93], v[150:153], v[216:219], v[90:93]
	v_mfma_f32_16x16x32_bf16 v[86:89], v[158:161], v[216:219], v[86:89]
	s_setprio 0
	s_setprio 1
	v_mfma_f32_16x16x32_bf16 v[114:117], v[162:165], v[178:181], 0
	v_mfma_f32_16x16x32_bf16 v[110:113], v[170:173], v[178:181], 0
	v_mfma_f32_16x16x32_bf16 v[98:101], v[162:165], v[186:189], 0
	v_mfma_f32_16x16x32_bf16 v[94:97], v[170:173], v[186:189], 0
	v_mfma_f32_16x16x32_bf16 v[82:85], v[162:165], v[194:197], 0
	v_mfma_f32_16x16x32_bf16 v[78:81], v[170:173], v[194:197], 0
	v_mfma_f32_16x16x32_bf16 v[74:77], v[162:165], v[212:215], 0
	v_mfma_f32_16x16x32_bf16 v[70:73], v[170:173], v[212:215], 0
	v_mfma_f32_16x16x32_bf16 v[114:117], v[166:169], v[182:185], v[114:117]
	v_mfma_f32_16x16x32_bf16 v[110:113], v[174:177], v[182:185], v[110:113]
	v_mfma_f32_16x16x32_bf16 v[98:101], v[166:169], v[190:193], v[98:101]
	v_mfma_f32_16x16x32_bf16 v[94:97], v[174:177], v[190:193], v[94:97]
	v_mfma_f32_16x16x32_bf16 v[82:85], v[166:169], v[198:201], v[82:85]
	v_mfma_f32_16x16x32_bf16 v[78:81], v[174:177], v[198:201], v[78:81]
	v_mfma_f32_16x16x32_bf16 v[74:77], v[166:169], v[216:219], v[74:77]
	v_mfma_f32_16x16x32_bf16 v[70:73], v[174:177], v[216:219], v[70:73]
	s_barrier
	s_setprio 0
	s_add_i32 s22, s66, s39
	v_lshl_add_u64 v[220:221], s[64:65], 0, v[0:1]
	s_mov_b32 m0, s22
	ds_read_b128 v[178:181], v144 offset:16384
	ds_read_b128 v[182:185], v144 offset:17408
	ds_read_b128 v[186:189], v144 offset:18432
	ds_read_b128 v[190:193], v144 offset:19456
	ds_read_b128 v[194:197], v144 offset:20480
	ds_read_b128 v[198:201], v144 offset:21504
	ds_read_b128 v[212:215], v144 offset:22528
	ds_read_b128 v[216:219], v144 offset:23552
	global_load_lds_dwordx4 v[220:221], off
	s_add_i32 m0, s22, 0x2000
	s_add_u32 s22, s64, s31
	v_lshl_add_u64 v[222:223], s[64:65], 0, v[14:15]
	s_addc_u32 s23, s65, 0
	s_add_i32 s64, s67, s39
	global_load_lds_dwordx4 v[222:223], off
	v_lshl_add_u64 v[224:225], s[22:23], 0, v[0:1]
	s_mov_b32 m0, s64
	v_lshl_add_u64 v[226:227], s[22:23], 0, v[14:15]
	global_load_lds_dwordx4 v[224:225], off
	s_add_i32 m0, s64, 0x2000
	v_lshl_add_u64 v[228:229], s[42:43], 0, v[136:137]
	global_load_lds_dwordx4 v[226:227], off
	s_mov_b32 m0, s47
	v_lshl_add_u64 v[244:245], s[42:43], 0, v[134:135]
	global_load_lds_dwordx4 v[228:229], off
	s_mov_b32 m0, s48
	s_nop 0
	global_load_lds_dwordx4 v[244:245], off
	s_waitcnt vmcnt(8)
	s_waitcnt lgkmcnt(0)
	s_setprio 1
	s_barrier
; #define PG8_STAGE(bufoff, gbase, voff) do { _Pragma("unroll") for (int _i = 0; _i < 2; ++_i) \
;         __builtin_amdgcn_global_load_lds((const unsigned*)((const char*)(gbase) + (voff)[_i]), (LAS unsigned*)(lds + (bufoff) + ldsw + _i * 8192), 16, 0, 0); } while (0)
; #define PG8_LDA(dst, b, h) do { _Pragma("unroll") for (int m = 0; m < 4; ++m) _Pragma("unroll") for (int k = 0; k < 2; ++k) dst[m][k] = *(const LAS bf16x8*)(lds + PG8_SA(b, h) + aoff + m * 2048 + k * 1024); } while (0)
; #define PG8_LDB(dst, b, h) do { _Pragma("unroll") for (int n = 0; n < 2; ++n) _Pragma("unroll") for (int k = 0; k < 2; ++k) dst[n][k] = *(const LAS bf16x8*)(lds + PG8_SB(b, h) + boff + n * 2048 + k * 1024); } while (0)
; #define PG8_MMA(ai, bj, At, Bt) do { __builtin_amdgcn_s_setprio(1); _Pragma("unroll") for (int m = 0; m < 4; ++m) _Pragma("unroll") for (int n = 0; n < 2; ++n) _Pragma("unroll") for (int k = 0; k < 2; ++k) \
;         acc[ai][bj][m][n] = __builtin_amdgcn_mfma_f32_16x16x32_bf16(Bt[n][k], At[m][k], acc[ai][bj][m][n], 0, 0, 0); __builtin_amdgcn_s_setprio(0); } while (0)
; #define PG8_WAIT_V(n) asm volatile("s_waitcnt vmcnt(" #n ")" ::: "memory")
; #define PG8_WAIT_L(n) asm volatile("s_waitcnt lgkmcnt(" #n ")" ::: "memory")
; #define PG8_BAR __builtin_amdgcn_s_barrier()
; #define PG8_SCHED __builtin_amdgcn_sched_barrier(0)
; template <class Epi, bool SEG>
; __device__ __forceinline__ void gemm_phase(LAS unsigned char* lds, const Gemm g, const int G, const int cidx, const Epi& E) {
;     ...
;             PG8_WAIT_V(8); PG8_WAIT_L(0); PG8_BAR; PG8_MMA(0, 0, At, B0); PG8_MMA(0, 1, At, B1); PG8_BAR; PG8_SCHED;
;             PG8_LDA(At, 0, 1); PG8_STAGE(PG8_SB(0, 0), b2, voffB); PG8_STAGE(PG8_SB(0, 1), b2 + hstepB, voffB); PG8_STAGE(PG8_SA(0, 0), a2, voffA);
;             PG8_WAIT_V(8); PG8_WAIT_L(0); PG8_BAR; PG8_MMA(1, 0, At, B0); PG8_MMA(1, 1, At, B1); PG8_BAR; PG8_SCHED;
;             PG8_LDB(B0, 1, 0); PG8_LDB(B1, 1, 1); PG8_SCHED; PG8_LDA(At, 1, 0); PG8_STAGE(PG8_SA(0, 1), a2 + hstepA, voffA);
;             PG8_WAIT_V(8); PG8_WAIT_L(0); PG8_BAR; PG8_MMA(0, 0, At, B0); PG8_MMA(0, 1, At, B1); PG8_BAR; PG8_SCHED;
	v_mfma_f32_16x16x32_bf16 v[66:69], v[146:149], v[178:181], 0
	v_mfma_f32_16x16x32_bf16 v[62:65], v[154:157], v[178:181], 0
	v_mfma_f32_16x16x32_bf16 v[58:61], v[146:149], v[186:189], 0
	v_mfma_f32_16x16x32_bf16 v[54:57], v[154:157], v[186:189], 0
	v_mfma_f32_16x16x32_bf16 v[42:45], v[146:149], v[194:197], 0
	v_mfma_f32_16x16x32_bf16 v[38:41], v[154:157], v[194:197], 0
	v_mfma_f32_16x16x32_bf16 v[26:29], v[146:149], v[212:215], 0
	v_mfma_f32_16x16x32_bf16 v[22:25], v[154:157], v[212:215], 0
	v_mfma_f32_16x16x32_bf16 v[66:69], v[150:153], v[182:185], v[66:69]
	v_mfma_f32_16x16x32_bf16 v[62:65], v[158:161], v[182:185], v[62:65]
	v_mfma_f32_16x16x32_bf16 v[58:61], v[150:153], v[190:193], v[58:61]
	v_mfma_f32_16x16x32_bf16 v[54:57], v[158:161], v[190:193], v[54:57]
	v_mfma_f32_16x16x32_bf16 v[42:45], v[150:153], v[198:201], v[42:45]
	v_mfma_f32_16x16x32_bf16 v[38:41], v[158:161], v[198:201], v[38:41]
	v_mfma_f32_16x16x32_bf16 v[26:29], v[150:153], v[216:219], v[26:29]
	v_mfma_f32_16x16x32_bf16 v[22:25], v[158:161], v[216:219], v[22:25]
	s_setprio 0
	s_setprio 1
	v_mfma_f32_16x16x32_bf16 v[50:53], v[162:165], v[178:181], 0
	v_mfma_f32_16x16x32_bf16 v[46:49], v[170:173], v[178:181], 0
	v_mfma_f32_16x16x32_bf16 v[34:37], v[162:165], v[186:189], 0
	v_mfma_f32_16x16x32_bf16 v[30:33], v[170:173], v[186:189], 0
	v_mfma_f32_16x16x32_bf16 v[18:21], v[162:165], v[194:197], 0
	v_mfma_f32_16x16x32_bf16 v[10:13], v[170:173], v[194:197], 0
	v_mfma_f32_16x16x32_bf16 v[6:9], v[162:165], v[212:215], 0
	v_mfma_f32_16x16x32_bf16 v[2:5], v[170:173], v[212:215], 0
	v_mfma_f32_16x16x32_bf16 v[50:53], v[166:169], v[182:185], v[50:53]
	v_mfma_f32_16x16x32_bf16 v[46:49], v[174:177], v[182:185], v[46:49]
	v_mfma_f32_16x16x32_bf16 v[34:37], v[166:169], v[190:193], v[34:37]
	v_mfma_f32_16x16x32_bf16 v[30:33], v[174:177], v[190:193], v[30:33]
	v_mfma_f32_16x16x32_bf16 v[18:21], v[166:169], v[198:201], v[18:21]
	v_mfma_f32_16x16x32_bf16 v[10:13], v[174:177], v[198:201], v[10:13]
	v_mfma_f32_16x16x32_bf16 v[6:9], v[166:169], v[216:219], v[6:9]
	v_mfma_f32_16x16x32_bf16 v[2:5], v[174:177], v[216:219], v[2:5]
	s_barrier
	s_setprio 0
	s_add_i32 s64, 0, 0x18000
	v_add_u32_e32 v145, s64, v142
	s_add_i32 s65, 0, 0x1c000
	ds_read_b128 v[146:149], v145
	ds_read_b128 v[150:153], v145 offset:1024
	ds_read_b128 v[154:157], v145 offset:2048
	ds_read_b128 v[158:161], v145 offset:3072
	v_add_u32_e32 v145, s65, v142
	ds_read_b128 v[162:165], v145
	ds_read_b128 v[166:169], v145 offset:1024
	ds_read_b128 v[170:173], v145 offset:2048
	ds_read_b128 v[174:177], v145 offset:3072
	s_add_u32 s22, s42, 0x30000
	s_addc_u32 s23, s43, 0
	s_mov_b32 m0, s49
	v_lshl_add_u64 v[246:247], s[22:23], 0, v[136:137]
	ds_read_b128 v[178:181], v144 offset:32768
	ds_read_b128 v[182:185], v144 offset:33792
	ds_read_b128 v[186:189], v144 offset:34816
	ds_read_b128 v[190:193], v144 offset:35840
	ds_read_b128 v[194:197], v144 offset:36864
	ds_read_b128 v[198:201], v144 offset:37888
	ds_read_b128 v[212:215], v144 offset:38912
	ds_read_b128 v[216:219], v144 offset:39936
	global_load_lds_dwordx4 v[246:247], off
	v_lshl_add_u64 v[246:247], s[22:23], 0, v[134:135]
	s_mov_b32 m0, s50
	s_nop 0
	global_load_lds_dwordx4 v[246:247], off
	s_waitcnt vmcnt(8)
	s_waitcnt lgkmcnt(0)
	s_setprio 1
	s_barrier
	v_mfma_f32_16x16x32_bf16 v[130:133], v[146:149], v[178:181], v[130:133]
	v_mfma_f32_16x16x32_bf16 v[126:129], v[154:157], v[178:181], v[126:129]
	v_mfma_f32_16x16x32_bf16 v[122:125], v[146:149], v[186:189], v[122:125]
	v_mfma_f32_16x16x32_bf16 v[118:121], v[154:157], v[186:189], v[118:121]
	v_mfma_f32_16x16x32_bf16 v[106:109], v[146:149], v[194:197], v[106:109]
	v_mfma_f32_16x16x32_bf16 v[102:105], v[154:157], v[194:197], v[102:105]
	v_mfma_f32_16x16x32_bf16 v[90:93], v[146:149], v[212:215], v[90:93]
	v_mfma_f32_16x16x32_bf16 v[86:89], v[154:157], v[212:215], v[86:89]
	v_mfma_f32_16x16x32_bf16 v[130:133], v[150:153], v[182:185], v[130:133]
	v_mfma_f32_16x16x32_bf16 v[126:129], v[158:161], v[182:185], v[126:129]
	v_mfma_f32_16x16x32_bf16 v[122:125], v[150:153], v[190:193], v[122:125]
	v_mfma_f32_16x16x32_bf16 v[118:121], v[158:161], v[190:193], v[118:121]
	v_mfma_f32_16x16x32_bf16 v[106:109], v[150:153], v[198:201], v[106:109]
	v_mfma_f32_16x16x32_bf16 v[102:105], v[158:161], v[198:201], v[102:105]
	v_mfma_f32_16x16x32_bf16 v[90:93], v[150:153], v[216:219], v[90:93]
	v_mfma_f32_16x16x32_bf16 v[86:89], v[158:161], v[216:219], v[86:89]
	s_setprio 0
	s_setprio 1
	v_mfma_f32_16x16x32_bf16 v[114:117], v[162:165], v[178:181], v[114:117]
	v_mfma_f32_16x16x32_bf16 v[110:113], v[170:173], v[178:181], v[110:113]
	v_mfma_f32_16x16x32_bf16 v[98:101], v[162:165], v[186:189], v[98:101]
	v_mfma_f32_16x16x32_bf16 v[94:97], v[170:173], v[186:189], v[94:97]
	v_mfma_f32_16x16x32_bf16 v[82:85], v[162:165], v[194:197], v[82:85]
	v_mfma_f32_16x16x32_bf16 v[78:81], v[170:173], v[194:197], v[78:81]
	v_mfma_f32_16x16x32_bf16 v[74:77], v[162:165], v[212:215], v[74:77]
	v_mfma_f32_16x16x32_bf16 v[70:73], v[170:173], v[212:215], v[70:73]
	v_mfma_f32_16x16x32_bf16 v[114:117], v[166:169], v[182:185], v[114:117]
	v_mfma_f32_16x16x32_bf16 v[110:113], v[174:177], v[182:185], v[110:113]
	v_mfma_f32_16x16x32_bf16 v[98:101], v[166:169], v[190:193], v[98:101]
	v_mfma_f32_16x16x32_bf16 v[94:97], v[174:177], v[190:193], v[94:97]
	v_mfma_f32_16x16x32_bf16 v[82:85], v[166:169], v[198:201], v[82:85]
	v_mfma_f32_16x16x32_bf16 v[78:81], v[174:177], v[198:201], v[78:81]
	v_mfma_f32_16x16x32_bf16 v[74:77], v[166:169], v[216:219], v[74:77]
	v_mfma_f32_16x16x32_bf16 v[70:73], v[174:177], v[216:219], v[70:73]
	s_barrier
; #define PG8_STAGE(bufoff, gbase, voff) do { _Pragma("unroll") for (int _i = 0; _i < 2; ++_i) \
;         __builtin_amdgcn_global_load_lds((const unsigned*)((const char*)(gbase) + (voff)[_i]), (LAS unsigned*)(lds + (bufoff) + ldsw + _i * 8192), 16, 0, 0); } while (0)
; #define PG8_LDA(dst, b, h) do { _Pragma("unroll") for (int m = 0; m < 4; ++m) _Pragma("unroll") for (int k = 0; k < 2; ++k) dst[m][k] = *(const LAS bf16x8*)(lds + PG8_SA(b, h) + aoff + m * 2048 + k * 1024); } while (0)
; #define PG8_MMA(ai, bj, At, Bt) do { __builtin_amdgcn_s_setprio(1); _Pragma("unroll") for (int m = 0; m < 4; ++m) _Pragma("unroll") for (int n = 0; n < 2; ++n) _Pragma("unroll") for (int k = 0; k < 2; ++k) \
;         acc[ai][bj][m][n] = __builtin_amdgcn_mfma_f32_16x16x32_bf16(Bt[n][k], At[m][k], acc[ai][bj][m][n], 0, 0, 0); __builtin_amdgcn_s_setprio(0); } while (0)
; #define PG8_WAIT_V(n) asm volatile("s_waitcnt vmcnt(" #n ")" ::: "memory")
; #define PG8_WAIT_L(n) asm volatile("s_waitcnt lgkmcnt(" #n ")" ::: "memory")
; #define PG8_BAR __builtin_amdgcn_s_barrier()
; #define PG8_SCHED __builtin_amdgcn_sched_barrier(0)
; template <class Epi, bool SEG>
; __device__ __forceinline__ void gemm_phase(LAS unsigned char* lds, const Gemm g, const int G, const int cidx, const Epi& E) {
;     ...
;             PG8_WAIT_V(8); PG8_WAIT_L(0); PG8_BAR; PG8_MMA(0, 0, At, B0); PG8_MMA(0, 1, At, B1); PG8_BAR; PG8_SCHED;
;             PG8_LDA(At, 1, 1); PG8_STAGE(PG8_SB(1, 0), b3, voffB); PG8_STAGE(PG8_SB(1, 1), b3 + hstepB, voffB); PG8_STAGE(PG8_SA(1, 0), a3, voffA);
;             PG8_WAIT_V(8); PG8_WAIT_L(0); PG8_BAR; PG8_MMA(1, 0, At, B0); PG8_MMA(1, 1, At, B1); PG8_BAR; PG8_SCHED;
;         }
	s_setprio 0
	s_add_i32 s22, s64, s39
	v_lshl_add_u64 v[220:221], v[220:221], 0, s[28:29]
	s_mov_b32 m0, s22
	ds_read_b128 v[178:181], v144 offset:49152
	ds_read_b128 v[182:185], v144 offset:50176
	ds_read_b128 v[186:189], v144 offset:51200
	ds_read_b128 v[190:193], v144 offset:52224
	ds_read_b128 v[194:197], v144 offset:53248
	ds_read_b128 v[198:201], v144 offset:54272
	ds_read_b128 v[212:215], v144 offset:55296
	ds_read_b128 v[216:219], v144 offset:56320
	global_load_lds_dwordx4 v[220:221], off
	v_lshl_add_u64 v[220:221], v[222:223], 0, s[28:29]
	s_add_i32 m0, s22, 0x2000
	s_add_i32 s22, s65, s39
	global_load_lds_dwordx4 v[220:221], off
	v_lshl_add_u64 v[220:221], v[224:225], 0, s[28:29]
	s_mov_b32 m0, s22
	s_nop 0
	global_load_lds_dwordx4 v[220:221], off
	v_lshl_add_u64 v[220:221], v[226:227], 0, s[28:29]
	s_add_i32 m0, s22, 0x2000
	s_nop 0
	global_load_lds_dwordx4 v[220:221], off
	v_lshl_add_u64 v[220:221], v[228:229], 0, s[28:29]
	s_mov_b32 m0, s55
	s_nop 0
	global_load_lds_dwordx4 v[220:221], off
	v_lshl_add_u64 v[220:221], v[244:245], 0, s[28:29]
	s_mov_b32 m0, s56
	s_nop 0
	global_load_lds_dwordx4 v[220:221], off
	s_waitcnt vmcnt(8)
	s_waitcnt lgkmcnt(0)
	s_setprio 1
	s_barrier
	v_mfma_f32_16x16x32_bf16 v[66:69], v[146:149], v[178:181], v[66:69]
	v_mfma_f32_16x16x32_bf16 v[62:65], v[154:157], v[178:181], v[62:65]
	v_mfma_f32_16x16x32_bf16 v[58:61], v[146:149], v[186:189], v[58:61]
	v_mfma_f32_16x16x32_bf16 v[54:57], v[154:157], v[186:189], v[54:57]
	v_mfma_f32_16x16x32_bf16 v[42:45], v[146:149], v[194:197], v[42:45]
	v_mfma_f32_16x16x32_bf16 v[38:41], v[154:157], v[194:197], v[38:41]
	v_mfma_f32_16x16x32_bf16 v[26:29], v[146:149], v[212:215], v[26:29]
	v_mfma_f32_16x16x32_bf16 v[22:25], v[154:157], v[212:215], v[22:25]
	v_mfma_f32_16x16x32_bf16 v[66:69], v[150:153], v[182:185], v[66:69]
	v_mfma_f32_16x16x32_bf16 v[62:65], v[158:161], v[182:185], v[62:65]
	v_mfma_f32_16x16x32_bf16 v[58:61], v[150:153], v[190:193], v[58:61]
	v_mfma_f32_16x16x32_bf16 v[54:57], v[158:161], v[190:193], v[54:57]
	v_mfma_f32_16x16x32_bf16 v[42:45], v[150:153], v[198:201], v[42:45]
	v_mfma_f32_16x16x32_bf16 v[38:41], v[158:161], v[198:201], v[38:41]
	v_mfma_f32_16x16x32_bf16 v[26:29], v[150:153], v[216:219], v[26:29]
	v_mfma_f32_16x16x32_bf16 v[22:25], v[158:161], v[216:219], v[22:25]
	s_setprio 0
	s_setprio 1
	v_mfma_f32_16x16x32_bf16 v[50:53], v[162:165], v[178:181], v[50:53]
	v_mfma_f32_16x16x32_bf16 v[46:49], v[170:173], v[178:181], v[46:49]
	v_mfma_f32_16x16x32_bf16 v[34:37], v[162:165], v[186:189], v[34:37]
	v_mfma_f32_16x16x32_bf16 v[30:33], v[170:173], v[186:189], v[30:33]
	v_mfma_f32_16x16x32_bf16 v[18:21], v[162:165], v[194:197], v[18:21]
	v_mfma_f32_16x16x32_bf16 v[10:13], v[170:173], v[194:197], v[10:13]
	v_mfma_f32_16x16x32_bf16 v[6:9], v[162:165], v[212:215], v[6:9]
	v_mfma_f32_16x16x32_bf16 v[2:5], v[170:173], v[212:215], v[2:5]
	v_mfma_f32_16x16x32_bf16 v[50:53], v[166:169], v[182:185], v[50:53]
	v_mfma_f32_16x16x32_bf16 v[46:49], v[174:177], v[182:185], v[46:49]
	v_mfma_f32_16x16x32_bf16 v[34:37], v[166:169], v[190:193], v[34:37]
	v_mfma_f32_16x16x32_bf16 v[30:33], v[174:177], v[190:193], v[30:33]
	v_mfma_f32_16x16x32_bf16 v[18:21], v[166:169], v[198:201], v[18:21]
	v_mfma_f32_16x16x32_bf16 v[10:13], v[174:177], v[198:201], v[10:13]
	v_mfma_f32_16x16x32_bf16 v[6:9], v[166:169], v[216:219], v[6:9]
	v_mfma_f32_16x16x32_bf16 v[2:5], v[174:177], v[216:219], v[2:5]
	s_barrier
	s_setprio 0
	s_add_u32 s61, s61, 0x100
	s_addc_u32 s62, s62, 0
	s_mov_b64 s[22:23], s[40:41]
	s_mov_b32 s42, s63
